# attention: first tile pair (t=0) also runs through the hand-written loop with reference 0, then one signed power-of-two re-reference
# speedup vs baseline: 1.0120x; 1.0049x over previous
.LBB0_834:
	s_branch .Latt_iter
	s_and_b32 s42, s35, 2
	s_mul_i32 s2, s42, 0x3400
	v_add_u32_e32 v0, s2, v209
	ds_read_b128 v[2:5], v0 offset:6656
	ds_read_b128 v[6:9], v0 offset:6688
	s_cmp_lg_u32 s35, 0
	s_waitcnt vmcnt(5) lgkmcnt(1)
	v_mfma_f32_32x32x16_bf16 v[98:113], v[2:5], v[154:157], 0
	s_waitcnt vmcnt(4) lgkmcnt(0)
	v_mfma_f32_32x32x16_bf16 v[98:113], v[6:9], v[158:161], v[98:113]
	ds_read_b128 v[2:5], v0 offset:6720
	ds_read_b128 v[6:9], v0 offset:6752
	s_waitcnt vmcnt(3) lgkmcnt(1)
	v_mfma_f32_32x32x16_bf16 v[98:113], v[2:5], v[162:165], v[98:113]
	s_waitcnt vmcnt(2) lgkmcnt(0)
	v_mfma_f32_32x32x16_bf16 v[98:113], v[6:9], v[166:169], v[98:113]
	ds_read_b128 v[2:5], v0 offset:6784
	ds_read_b128 v[6:9], v0 offset:6816
	s_waitcnt vmcnt(1) lgkmcnt(1)
	v_mfma_f32_32x32x16_bf16 v[98:113], v[2:5], v[170:173], v[98:113]
	ds_read_b128 v[2:5], v0 offset:13312
	ds_read_b128 v[66:69], v0 offset:13344
	ds_read_b128 v[18:21], v0 offset:19968
	ds_read_b128 v[70:73], v0 offset:20000
	s_waitcnt vmcnt(0) lgkmcnt(4)
	v_mfma_f32_32x32x16_bf16 v[98:113], v[6:9], v[174:177], v[98:113]
	s_waitcnt lgkmcnt(3)
	v_mfma_f32_32x32x16_bf16 v[2:17], v[2:5], v[154:157], 0
	s_waitcnt lgkmcnt(1)
	v_mfma_f32_32x32x16_bf16 v[18:33], v[18:21], v[154:157], 0
	v_mfma_f32_32x32x16_bf16 v[2:17], v[66:69], v[158:161], v[2:17]
	s_waitcnt lgkmcnt(0)
	v_mfma_f32_32x32x16_bf16 v[18:33], v[70:73], v[158:161], v[18:33]
	ds_read_b128 v[66:69], v0 offset:13376
	ds_read_b128 v[70:73], v0 offset:13408
	s_waitcnt lgkmcnt(1)
	v_mfma_f32_32x32x16_bf16 v[2:17], v[66:69], v[162:165], v[2:17]
	ds_read_b128 v[66:69], v0 offset:20032
	ds_read_b128 v[74:77], v0 offset:20064
	s_waitcnt lgkmcnt(1)
	v_mfma_f32_32x32x16_bf16 v[18:33], v[66:69], v[162:165], v[18:33]
	v_mfma_f32_32x32x16_bf16 v[2:17], v[70:73], v[166:169], v[2:17]
	ds_read_b128 v[66:69], v0 offset:13440
	ds_read_b128 v[70:73], v0 offset:13472
	s_waitcnt lgkmcnt(2)
	v_mfma_f32_32x32x16_bf16 v[18:33], v[74:77], v[166:169], v[18:33]
	s_waitcnt lgkmcnt(1)
	v_mfma_f32_32x32x16_bf16 v[2:17], v[66:69], v[170:173], v[2:17]
	ds_read_b128 v[66:69], v0
	ds_read_b128 v[74:77], v0 offset:32
	s_waitcnt lgkmcnt(1)
	v_mfma_f32_32x32x16_bf16 v[114:129], v[66:69], v[154:157], 0
	s_waitcnt lgkmcnt(0)
	v_mfma_f32_32x32x16_bf16 v[114:129], v[74:77], v[158:161], v[114:129]
	ds_read_b128 v[66:69], v0 offset:64
	ds_read_b128 v[74:77], v0 offset:96
	s_waitcnt lgkmcnt(1)
	v_mfma_f32_32x32x16_bf16 v[114:129], v[66:69], v[162:165], v[114:129]
	s_waitcnt lgkmcnt(0)
	v_mfma_f32_32x32x16_bf16 v[114:129], v[74:77], v[166:169], v[114:129]
	ds_read_b128 v[66:69], v0 offset:128
	ds_read_b128 v[74:77], v0 offset:160
	s_waitcnt lgkmcnt(1)
	v_mfma_f32_32x32x16_bf16 v[114:129], v[66:69], v[170:173], v[114:129]
	s_waitcnt lgkmcnt(0)
	v_mfma_f32_32x32x16_bf16 v[114:129], v[74:77], v[174:177], v[114:129]
	ds_read_b128 v[66:69], v0 offset:20096
	ds_read_b128 v[74:77], v0 offset:20128
	s_waitcnt lgkmcnt(1)
	v_mfma_f32_32x32x16_bf16 v[18:33], v[66:69], v[170:173], v[18:33]
	s_nop 7
	v_max3_f32 v0, v114, v115, v98
	v_max3_f32 v78, v116, v117, v99
	v_max3_f32 v0, v0, v100, v101
	v_max3_f32 v0, v0, v118, v119
	v_max3_f32 v66, v78, v120, v121
	v_max3_f32 v0, v0, v102, v103
	v_max3_f32 v66, v66, v104, v105
	v_mfma_f32_32x32x16_bf16 v[2:17], v[70:73], v[174:177], v[2:17]
	v_max3_f32 v0, v0, v122, v123
	v_max3_f32 v66, v66, v124, v125
	v_max3_f32 v0, v0, v106, v107
	v_max3_f32 v66, v66, v108, v109
	v_max3_f32 v0, v0, v126, v127
	v_max3_f32 v66, v66, v128, v129
	v_max3_f32 v0, v0, v110, v111
	s_waitcnt lgkmcnt(0)
	v_mfma_f32_32x32x16_bf16 v[18:33], v[74:77], v[174:177], v[18:33]
	v_max3_f32 v66, v66, v112, v113
	v_max_f32_e32 v66, v66, v66
	v_max_f32_e32 v0, v0, v0
	v_max_f32_e32 v211, v0, v66
	s_cbranch_scc0 .LBB0_851
	v_and_b32_e32 v66, 64, v203
	v_xor_b32_e32 v0, 32, v203
	v_add_u32_e32 v66, 64, v66
	v_cmp_lt_i32_e32 vcc, v0, v66
	v_mov_b64_e32 v[96:97], v[64:65]
	v_mov_b32_e32 v212, v210
	v_cndmask_b32_e32 v0, v203, v0, vcc
	v_lshlrev_b32_e32 v0, 2, v0
	ds_bpermute_b32 v66, v0, v211
	v_mov_b32_e32 v0, v189
	v_mov_b64_e32 v[94:95], v[62:63]
	v_mov_b64_e32 v[92:93], v[60:61]
	v_mov_b64_e32 v[90:91], v[58:59]
	s_waitcnt lgkmcnt(0)
	v_max_f32_e32 v66, v66, v66
	v_max_f32_e32 v66, v211, v66
	v_sub_f32_e32 v178, v66, v189
	v_mov_b64_e32 v[80:81], v[48:49]
	v_cmp_lt_f32_e32 vcc, s70, v178
	v_mov_b64_e32 v[78:79], v[46:47]
	v_mov_b64_e32 v[76:77], v[44:45]
	v_mov_b64_e32 v[74:75], v[42:43]
	v_mov_b64_e32 v[72:73], v[40:41]
	v_mov_b64_e32 v[70:71], v[38:39]
	v_mov_b64_e32 v[68:69], v[36:37]
	v_mov_b64_e32 v[66:67], v[34:35]
	v_mov_b64_e32 v[88:89], v[56:57]
	v_mov_b64_e32 v[86:87], v[54:55]
	v_mov_b64_e32 v[84:85], v[52:53]
	v_mov_b64_e32 v[82:83], v[50:51]
	s_cbranch_vccz .LBB0_839
	v_max_f32_e32 v0, v178, v178
	v_max_f32_e32 v0, 0, v0
	v_exp_f32_e64 v66, -v0
	s_and_saveexec_b64 s[2:3], s[40:41]
	ds_write_b32 v207, v66
	s_or_b64 exec, exec, s[2:3]
	s_waitcnt lgkmcnt(0)
	ds_read_b128 v[82:85], v199 offset:64
	ds_read_b128 v[86:89], v199 offset:96
	ds_read_b128 v[178:181], v199
	ds_read_b128 v[214:217], v199 offset:32
	v_add_f32_e32 v0, v189, v0
	v_mul_f32_e32 v212, v210, v66
	s_waitcnt lgkmcnt(2)
	v_pk_mul_f32 v[80:81], v[48:49], v[88:89]
	v_pk_mul_f32 v[76:77], v[44:45], v[84:85]
	s_waitcnt lgkmcnt(0)
	v_pk_mul_f32 v[72:73], v[40:41], v[216:217]
	v_pk_mul_f32 v[68:69], v[36:37], v[180:181]
	v_pk_mul_f32 v[78:79], v[46:47], v[86:87]
	v_pk_mul_f32 v[74:75], v[42:43], v[82:83]
	v_pk_mul_f32 v[70:71], v[38:39], v[214:215]
	v_pk_mul_f32 v[66:67], v[34:35], v[178:179]
	v_pk_mul_f32 v[96:97], v[64:65], v[88:89]
	v_pk_mul_f32 v[92:93], v[60:61], v[84:85]
	v_pk_mul_f32 v[88:89], v[56:57], v[216:217]
	v_pk_mul_f32 v[84:85], v[52:53], v[180:181]
	v_pk_mul_f32 v[94:95], v[62:63], v[86:87]
	v_pk_mul_f32 v[90:91], v[58:59], v[82:83]
	v_pk_mul_f32 v[86:87], v[54:55], v[214:215]
	v_pk_mul_f32 v[82:83], v[50:51], v[178:179]

; __device__ __forceinline__ void attn_unit(LAS char* lds, const bf16_t* Qp, const bf16_t* KVp, const bf16_t* KRp, int ntiles, bf16_t* Yp, bool dry) {
;     ...
;     for (int t = 0; t < ntiles; t += 2) {
;         const int sb0 = (t & 2);
;         const bool more = (t + 2 < ntiles);
;         f32x16 pa0 = {}, pa1 = {}, pb0 = {}, pb1 = {};
;         AT_QK(sb0, pa0, pa1);
.Latt_iter:
	s_waitcnt vmcnt(0)
	v_xor_b32_e32 v82, 0x80000000, v189
	v_mov_b32_e32 v83, v82
	v_mov_b32_e32 v84, v82
	v_mov_b32_e32 v85, v82
	v_mov_b32_e32 v86, v82
	v_mov_b32_e32 v87, v82
	v_mov_b32_e32 v88, v82
	v_mov_b32_e32 v89, v82
	v_mov_b32_e32 v90, v82
	v_mov_b32_e32 v91, v82
	v_mov_b32_e32 v92, v82
	v_mov_b32_e32 v93, v82
	v_mov_b32_e32 v94, v82
	v_mov_b32_e32 v95, v82
	v_mov_b32_e32 v96, v82
	v_mov_b32_e32 v97, v82

.Latt_noload:
	ds_read_b128 v[66:69], v0 offset:0
	ds_read_b128 v[70:73], v0 offset:6656
	ds_read_b128 v[74:77], v0 offset:32
	ds_read_b128 v[78:81], v0 offset:6688
	ds_read_b128 v[212:215], v0 offset:64
	ds_read_b128 v[240:243], v0 offset:6720
	ds_read_b128 v[244:247], v0 offset:96
	s_waitcnt lgkmcnt(6)
	v_mfma_f32_32x32x16_bf16 v[114:129], v[66:69], v[154:157], v[82:97]
	ds_read_b128 v[248:251], v0 offset:6752
	s_waitcnt lgkmcnt(6)
	v_mfma_f32_32x32x16_bf16 v[98:113], v[70:73], v[154:157], v[82:97]
	ds_read_b128 v[66:69], v0 offset:128
	s_waitcnt lgkmcnt(6)
	v_mfma_f32_32x32x16_bf16 v[114:129], v[74:77], v[158:161], v[114:129]
	ds_read_b128 v[70:73], v0 offset:6784
	s_waitcnt lgkmcnt(6)
	v_mfma_f32_32x32x16_bf16 v[98:113], v[78:81], v[158:161], v[98:113]
	ds_read_b128 v[74:77], v0 offset:160
	s_waitcnt lgkmcnt(6)
	v_mfma_f32_32x32x16_bf16 v[114:129], v[212:215], v[162:165], v[114:129]
	ds_read_b128 v[78:81], v0 offset:6816
	s_waitcnt lgkmcnt(6)
	v_mfma_f32_32x32x16_bf16 v[98:113], v[240:243], v[162:165], v[98:113]
	ds_read_b128 v[212:215], v0 offset:13312
	s_waitcnt lgkmcnt(6)
	v_mfma_f32_32x32x16_bf16 v[114:129], v[244:247], v[166:169], v[114:129]
	ds_read_b128 v[240:243], v0 offset:19968
	s_waitcnt lgkmcnt(6)
	v_mfma_f32_32x32x16_bf16 v[98:113], v[248:251], v[166:169], v[98:113]
	ds_read_b128 v[244:247], v0 offset:13344
	s_waitcnt lgkmcnt(6)
	v_mfma_f32_32x32x16_bf16 v[114:129], v[66:69], v[170:173], v[114:129]
	ds_read_b128 v[248:251], v0 offset:20000
	s_waitcnt lgkmcnt(6)
	v_mfma_f32_32x32x16_bf16 v[98:113], v[70:73], v[170:173], v[98:113]
	ds_read_b128 v[66:69], v0 offset:13376
	s_waitcnt lgkmcnt(6)
	v_mfma_f32_32x32x16_bf16 v[114:129], v[74:77], v[174:177], v[114:129]
	ds_read_b128 v[70:73], v0 offset:20032
	s_waitcnt lgkmcnt(6)
	v_mfma_f32_32x32x16_bf16 v[98:113], v[78:81], v[174:177], v[98:113]
	ds_read_b128 v[74:77], v0 offset:13408
	s_waitcnt lgkmcnt(6)
	v_mfma_f32_32x32x16_bf16 v[2:17], v[212:215], v[154:157], v[82:97]
	ds_read_b128 v[78:81], v0 offset:20064
	s_waitcnt lgkmcnt(6)
	v_mfma_f32_32x32x16_bf16 v[18:33], v[240:243], v[154:157], v[82:97]
	ds_read_b128 v[212:215], v0 offset:13440
	s_waitcnt lgkmcnt(6)
	v_mfma_f32_32x32x16_bf16 v[2:17], v[244:247], v[158:161], v[2:17]
	ds_read_b128 v[240:243], v0 offset:20096
	s_waitcnt lgkmcnt(6)
	v_mfma_f32_32x32x16_bf16 v[18:33], v[248:251], v[158:161], v[18:33]
	ds_read_b128 v[244:247], v0 offset:13472
	s_waitcnt lgkmcnt(6)
	v_mfma_f32_32x32x16_bf16 v[2:17], v[66:69], v[162:165], v[2:17]
	ds_read_b128 v[248:251], v0 offset:20128
	s_waitcnt lgkmcnt(6)
	v_mfma_f32_32x32x16_bf16 v[18:33], v[70:73], v[162:165], v[18:33]
	ds_read_b64_tr_b16 v[216:217], v185 offset:53248
	ds_read_b64_tr_b16 v[218:219], v185 offset:53760
	s_waitcnt lgkmcnt(7)
	v_mfma_f32_32x32x16_bf16 v[2:17], v[74:77], v[166:169], v[2:17]
	ds_read_b64_tr_b16 v[220:221], v185 offset:57344
	ds_read_b64_tr_b16 v[222:223], v185 offset:57856
	s_waitcnt lgkmcnt(8)
	v_mfma_f32_32x32x16_bf16 v[18:33], v[78:81], v[166:169], v[18:33]
	ds_read_b64_tr_b16 v[224:225], v185 offset:54272
	ds_read_b64_tr_b16 v[226:227], v185 offset:54784
	s_waitcnt lgkmcnt(9)
	v_mfma_f32_32x32x16_bf16 v[2:17], v[212:215], v[170:173], v[2:17]
	ds_read_b64_tr_b16 v[228:229], v185 offset:58368
	ds_read_b64_tr_b16 v[230:231], v185 offset:58880
	s_waitcnt lgkmcnt(10)
	v_mfma_f32_32x32x16_bf16 v[18:33], v[240:243], v[170:173], v[18:33]
	ds_read_b64_tr_b16 v[232:233], v185 offset:55296
	ds_read_b64_tr_b16 v[234:235], v185 offset:55808
	s_waitcnt lgkmcnt(11)
	v_mfma_f32_32x32x16_bf16 v[2:17], v[244:247], v[174:177], v[2:17]
	ds_read_b64_tr_b16 v[236:237], v185 offset:59392
	ds_read_b64_tr_b16 v[238:239], v185 offset:59904
	s_waitcnt lgkmcnt(12)
	v_mfma_f32_32x32x16_bf16 v[18:33], v[248:251], v[174:177], v[18:33]
	v_exp_f32_e32 v114, v114
	v_exp_f32_e32 v115, v115
	v_exp_f32_e32 v116, v116
	v_exp_f32_e32 v117, v117
	v_exp_f32_e32 v118, v118
	v_exp_f32_e32 v119, v119
	v_exp_f32_e32 v120, v120
	v_exp_f32_e32 v121, v121
	v_cvt_pk_bf16_f32 v66, v114, v115
	v_cvt_pk_bf16_f32 v67, v116, v117
	v_cvt_pk_bf16_f32 v68, v118, v119
	v_cvt_pk_bf16_f32 v69, v120, v121
	v_add_f32_e32 v178, v114, v115
	v_add_f32_e32 v179, v116, v117
	v_add_f32_e32 v180, v118, v119
	v_add_f32_e32 v181, v120, v121
	v_add_f32_e32 v178, v178, v179
	v_add_f32_e32 v180, v180, v181
	v_add_f32_e32 v178, v178, v180
	v_add_f32_e32 v210, v210, v178
	ds_read_b64_tr_b16 v[240:241], v185 offset:56320
	ds_read_b64_tr_b16 v[242:243], v185 offset:56832
	ds_read_b64_tr_b16 v[244:245], v185 offset:60416
	s_waitcnt lgkmcnt(11)
	ds_read_b64_tr_b16 v[246:247], v185 offset:60928
	ds_read_b64_tr_b16 v[114:115], v184 offset:53248
	ds_read_b64_tr_b16 v[116:117], v184 offset:53760
	ds_read_b64_tr_b16 v[118:119], v184 offset:57344
	s_waitcnt lgkmcnt(11)
	ds_read_b64_tr_b16 v[120:121], v184 offset:57856
	v_exp_f32_e32 v122, v122
	v_exp_f32_e32 v123, v123
	v_exp_f32_e32 v124, v124
	v_mfma_f32_32x32x16_bf16 v[34:49], v[66:69], v[216:219], v[34:49]
	v_exp_f32_e32 v125, v125
	v_exp_f32_e32 v126, v126
	v_exp_f32_e32 v127, v127
	v_exp_f32_e32 v128, v128
	v_exp_f32_e32 v129, v129
	v_cvt_pk_bf16_f32 v70, v122, v123
	v_cvt_pk_bf16_f32 v71, v124, v125
	v_mfma_f32_32x32x16_bf16 v[50:65], v[66:69], v[220:223], v[50:65]
	v_cvt_pk_bf16_f32 v72, v126, v127
	v_cvt_pk_bf16_f32 v73, v128, v129
	v_add_f32_e32 v178, v122, v123
	v_add_f32_e32 v179, v124, v125
	v_add_f32_e32 v180, v126, v127
	v_add_f32_e32 v181, v128, v129
	v_add_f32_e32 v178, v178, v179
	v_add_f32_e32 v180, v180, v181
	v_add_f32_e32 v178, v178, v180
	v_add_f32_e32 v210, v210, v178
	ds_read_b64_tr_b16 v[122:123], v184 offset:54272
	ds_read_b64_tr_b16 v[124:125], v184 offset:54784
	ds_read_b64_tr_b16 v[126:127], v184 offset:58368
	s_waitcnt lgkmcnt(11)
	ds_read_b64_tr_b16 v[128:129], v184 offset:58880
	v_exp_f32_e32 v98, v98
	v_exp_f32_e32 v99, v99
	v_exp_f32_e32 v100, v100
	v_mfma_f32_32x32x16_bf16 v[34:49], v[70:73], v[224:227], v[34:49]
	v_exp_f32_e32 v101, v101
	v_exp_f32_e32 v102, v102
	v_exp_f32_e32 v103, v103
	v_exp_f32_e32 v104, v104
	v_exp_f32_e32 v105, v105
	v_cvt_pk_bf16_f32 v74, v98, v99
	v_cvt_pk_bf16_f32 v75, v100, v101
	v_mfma_f32_32x32x16_bf16 v[50:65], v[70:73], v[228:231], v[50:65]
	v_cvt_pk_bf16_f32 v76, v102, v103
	v_cvt_pk_bf16_f32 v77, v104, v105
	v_add_f32_e32 v178, v98, v99
	v_add_f32_e32 v179, v100, v101
	v_add_f32_e32 v180, v102, v103
	v_add_f32_e32 v181, v104, v105
	v_add_f32_e32 v178, v178, v179
	v_add_f32_e32 v180, v180, v181
	v_add_f32_e32 v178, v178, v180
	v_add_f32_e32 v210, v210, v178
	ds_read_b64_tr_b16 v[98:99], v184 offset:55296
	ds_read_b64_tr_b16 v[100:101], v184 offset:55808
	ds_read_b64_tr_b16 v[102:103], v184 offset:59392
	s_waitcnt lgkmcnt(11)
	ds_read_b64_tr_b16 v[104:105], v184 offset:59904
	v_exp_f32_e32 v106, v106
	v_exp_f32_e32 v107, v107
	v_exp_f32_e32 v108, v108
	v_mfma_f32_32x32x16_bf16 v[34:49], v[74:77], v[232:235], v[34:49]
	v_exp_f32_e32 v109, v109
	v_exp_f32_e32 v110, v110
	v_exp_f32_e32 v111, v111
	v_exp_f32_e32 v112, v112
	v_exp_f32_e32 v113, v113
	v_cvt_pk_bf16_f32 v78, v106, v107
	v_cvt_pk_bf16_f32 v79, v108, v109
	v_mfma_f32_32x32x16_bf16 v[50:65], v[74:77], v[236:239], v[50:65]
	v_cvt_pk_bf16_f32 v80, v110, v111
	v_cvt_pk_bf16_f32 v81, v112, v113
	v_add_f32_e32 v178, v106, v107
	v_add_f32_e32 v179, v108, v109
	v_add_f32_e32 v180, v110, v111
	v_add_f32_e32 v181, v112, v113
	v_add_f32_e32 v178, v178, v179
	v_add_f32_e32 v180, v180, v181
	v_add_f32_e32 v178, v178, v180
	v_add_f32_e32 v210, v210, v178
	ds_read_b64_tr_b16 v[106:107], v184 offset:56320
	ds_read_b64_tr_b16 v[108:109], v184 offset:56832
	ds_read_b64_tr_b16 v[110:111], v184 offset:60416
	s_waitcnt lgkmcnt(11)
	ds_read_b64_tr_b16 v[112:113], v184 offset:60928
	v_exp_f32_e32 v2, v2
	v_exp_f32_e32 v3, v3
	v_exp_f32_e32 v4, v4
	v_mfma_f32_32x32x16_bf16 v[34:49], v[78:81], v[240:243], v[34:49]
	v_exp_f32_e32 v5, v5
	v_exp_f32_e32 v6, v6
	v_exp_f32_e32 v7, v7
	v_exp_f32_e32 v8, v8
	v_exp_f32_e32 v9, v9
	v_cvt_pk_bf16_f32 v66, v2, v3
	v_cvt_pk_bf16_f32 v67, v4, v5
	v_mfma_f32_32x32x16_bf16 v[50:65], v[78:81], v[244:247], v[50:65]
	v_cvt_pk_bf16_f32 v68, v6, v7
	v_cvt_pk_bf16_f32 v69, v8, v9
	v_add_f32_e32 v178, v2, v3
	v_add_f32_e32 v179, v4, v5
	v_add_f32_e32 v180, v6, v7
	v_add_f32_e32 v181, v8, v9
	v_add_f32_e32 v178, v178, v179
	v_add_f32_e32 v180, v180, v181
	v_add_f32_e32 v178, v178, v180
	v_add_f32_e32 v210, v210, v178
	v_exp_f32_e32 v10, v10
	v_exp_f32_e32 v11, v11
	v_exp_f32_e32 v12, v12
	v_mfma_f32_32x32x16_bf16 v[34:49], v[66:69], v[114:117], v[34:49]
	v_exp_f32_e32 v13, v13
	v_exp_f32_e32 v14, v14
	v_exp_f32_e32 v15, v15
	v_exp_f32_e32 v16, v16
	v_exp_f32_e32 v17, v17
	v_cvt_pk_bf16_f32 v70, v10, v11
	v_cvt_pk_bf16_f32 v71, v12, v13
	v_mfma_f32_32x32x16_bf16 v[50:65], v[66:69], v[118:121], v[50:65]
	v_cvt_pk_bf16_f32 v72, v14, v15
	v_cvt_pk_bf16_f32 v73, v16, v17
	v_add_f32_e32 v178, v10, v11
	v_add_f32_e32 v179, v12, v13
	v_add_f32_e32 v180, v14, v15
	v_add_f32_e32 v181, v16, v17
	v_add_f32_e32 v178, v178, v179
	v_add_f32_e32 v180, v180, v181
	v_add_f32_e32 v178, v178, v180
	v_add_f32_e32 v210, v210, v178
	v_exp_f32_e32 v18, v18
	v_exp_f32_e32 v19, v19
	v_exp_f32_e32 v20, v20
	s_waitcnt lgkmcnt(10)
	v_mfma_f32_32x32x16_bf16 v[34:49], v[70:73], v[122:125], v[34:49]
	v_exp_f32_e32 v21, v21
	v_exp_f32_e32 v22, v22
	v_exp_f32_e32 v23, v23
	v_exp_f32_e32 v24, v24
	v_exp_f32_e32 v25, v25
	v_cvt_pk_bf16_f32 v74, v18, v19
	v_cvt_pk_bf16_f32 v75, v20, v21
	s_waitcnt lgkmcnt(8)
	v_mfma_f32_32x32x16_bf16 v[50:65], v[70:73], v[126:129], v[50:65]
	v_cvt_pk_bf16_f32 v76, v22, v23
	v_cvt_pk_bf16_f32 v77, v24, v25
	v_add_f32_e32 v178, v18, v19
	v_add_f32_e32 v179, v20, v21
	v_add_f32_e32 v180, v22, v23
	v_add_f32_e32 v181, v24, v25
	v_add_f32_e32 v178, v178, v179
	v_add_f32_e32 v180, v180, v181
	v_add_f32_e32 v178, v178, v180
	v_add_f32_e32 v210, v210, v178
	v_exp_f32_e32 v26, v26
	v_exp_f32_e32 v27, v27
	v_exp_f32_e32 v28, v28
	s_waitcnt lgkmcnt(6)
	v_mfma_f32_32x32x16_bf16 v[34:49], v[74:77], v[98:101], v[34:49]
	v_exp_f32_e32 v29, v29
	v_exp_f32_e32 v30, v30
	v_exp_f32_e32 v31, v31
	v_exp_f32_e32 v32, v32
	v_exp_f32_e32 v33, v33
	v_cvt_pk_bf16_f32 v78, v26, v27
	v_cvt_pk_bf16_f32 v79, v28, v29
	s_waitcnt lgkmcnt(4)
	v_mfma_f32_32x32x16_bf16 v[50:65], v[74:77], v[102:105], v[50:65]
	v_cvt_pk_bf16_f32 v80, v30, v31
	v_cvt_pk_bf16_f32 v81, v32, v33
	v_add_f32_e32 v178, v26, v27
	v_add_f32_e32 v179, v28, v29
	v_add_f32_e32 v180, v30, v31
	v_add_f32_e32 v181, v32, v33
	v_add_f32_e32 v178, v178, v179
	v_add_f32_e32 v180, v180, v181
	v_add_f32_e32 v178, v178, v180
	v_add_f32_e32 v210, v210, v178
	s_waitcnt lgkmcnt(2)
	v_mfma_f32_32x32x16_bf16 v[34:49], v[78:81], v[106:109], v[34:49]
	s_waitcnt lgkmcnt(0)
	v_mfma_f32_32x32x16_bf16 v[50:65], v[78:81], v[110:113], v[50:65]
	s_cmp_eq_u32 s35, 0
	s_cbranch_scc1 .Latt_rs
	v_cmp_lt_f32_e32 vcc, 0x4b800000, v210
	s_cbranch_vccnz .Latt_rs

.Latt_rs:
	s_nop 15
	v_frexp_exp_i32_f32_e32 v211, v210
	v_mov_b32_e32 v179, v211
	s_nop 1
	v_permlane32_swap_b32_e32 v179, v211
	v_max_i32_e32 v211, v211, v179
	v_sub_u32_e32 v179, 0, v211
	v_cvt_f32_i32_e32 v178, v211
	v_ldexp_f32 v180, 1.0, v179
	s_and_saveexec_b64 s[2:3], s[40:41]
	ds_write_b32 v207, v180
	s_or_b64 exec, exec, s[2:3]
	s_waitcnt lgkmcnt(0)
	v_add_f32_e32 v189, v189, v178
	v_ldexp_f32 v210, v210, v179
	ds_read_b128 v[66:69], v199 offset:0
	ds_read_b128 v[70:73], v199 offset:32
	ds_read_b128 v[74:77], v199 offset:64
	ds_read_b128 v[78:81], v199 offset:96
	v_sub_f32_e32 v82, v82, v178
	v_sub_f32_e32 v83, v83, v178
	v_sub_f32_e32 v84, v84, v178
	v_sub_f32_e32 v85, v85, v178
	v_sub_f32_e32 v86, v86, v178
	v_sub_f32_e32 v87, v87, v178
	v_sub_f32_e32 v88, v88, v178
	v_sub_f32_e32 v89, v89, v178
	v_sub_f32_e32 v90, v90, v178
	v_sub_f32_e32 v91, v91, v178
	v_sub_f32_e32 v92, v92, v178
	v_sub_f32_e32 v93, v93, v178
	v_sub_f32_e32 v94, v94, v178
	v_sub_f32_e32 v95, v95, v178
	v_sub_f32_e32 v96, v96, v178
	v_sub_f32_e32 v97, v97, v178
	s_waitcnt lgkmcnt(0)
	v_mul_f32_e32 v34, v34, v66
	v_mul_f32_e32 v50, v50, v66
	v_mul_f32_e32 v35, v35, v67
	v_mul_f32_e32 v51, v51, v67
	v_mul_f32_e32 v36, v36, v68
	v_mul_f32_e32 v52, v52, v68
	v_mul_f32_e32 v37, v37, v69
	v_mul_f32_e32 v53, v53, v69
	v_mul_f32_e32 v38, v38, v70
	v_mul_f32_e32 v54, v54, v70
	v_mul_f32_e32 v39, v39, v71
	v_mul_f32_e32 v55, v55, v71
	v_mul_f32_e32 v40, v40, v72
	v_mul_f32_e32 v56, v56, v72
	v_mul_f32_e32 v41, v41, v73
	v_mul_f32_e32 v57, v57, v73
	v_mul_f32_e32 v42, v42, v74
	v_mul_f32_e32 v58, v58, v74
	v_mul_f32_e32 v43, v43, v75
	v_mul_f32_e32 v59, v59, v75
	v_mul_f32_e32 v44, v44, v76
	v_mul_f32_e32 v60, v60, v76
	v_mul_f32_e32 v45, v45, v77
	v_mul_f32_e32 v61, v61, v77
	v_mul_f32_e32 v46, v46, v78
	v_mul_f32_e32 v62, v62, v78
	v_mul_f32_e32 v47, v47, v79
	v_mul_f32_e32 v63, v63, v79
	v_mul_f32_e32 v48, v48, v80
	v_mul_f32_e32 v64, v64, v80
	v_mul_f32_e32 v49, v49, v81
	v_mul_f32_e32 v65, v65, v81
	s_nop 1
	s_branch .Latt_rsback
